# rwkv scan producer: no LDS drain (lgkmcnt) in front of the chunk loads
# baseline (speedup 1.0000x reference)
; __device__ __forceinline__ void rwkv_load_chunk(RwkvRegs& R, int n, int pw, int b, int col, const bf16_t* RKV, const bf16_t* LO, const bf16_t* Y) {
; #pragma unroll
;     for (int i = 0; i < 8; ++i) { const int tt = pw + 4 * i, m = b * T_ + 32 * n + tt; const bf16_t* zr = RKV + (size_t)m * RKV_LD; const bf16_t* lo = LO + (size_t)m * 2048;
;         R.vr[i] = zr[col]; R.vx[i] = zr[512 + col]; R.vv[i] = zr[1024 + col]; R.ve[i] = lo[col]; R.va[i] = lo[512 + col]; R.vk[i] = Y[(size_t)m * D_ + col]; }
; }
; __device__ __forceinline__ void rwkv_scan(const Ctx& c, const Params& p, int o, int nblk) {
;     ...
;                 if (n + 2 < 256) rwkv_load_chunk(R, n + 2, pw, b, col, RKV, LO, Y);
.LBB0_101:
	s_cmpk_gt_u32 s2, 0xfd
	s_cbranch_scc1 .LBB0_103
	s_add_i32 s11, s59, s72
	s_add_i32 s2, s11, 60
	s_mul_i32 s18, s2, 0xc00
	s_add_u32 s18, s16, s18
	s_addc_u32 s19, s17, 0
	s_lshl_b32 s62, s2, 12
	s_add_u32 s62, s12, s62
	s_addc_u32 s63, s13, 0
	s_lshl_b32 s2, s2, 11
	s_add_u32 s2, s74, s2
	s_addc_u32 s3, s75, 0
	global_load_ushort v10, v2, s[18:19]
	global_load_ushort v11, v2, s[18:19] offset:1024
	global_load_ushort v12, v2, s[18:19] offset:2048
	global_load_ushort v13, v2, s[62:63]
	global_load_ushort v14, v2, s[62:63] offset:1024
	global_load_ushort v15, v2, s[2:3]
	s_add_u32 s18, s18, 0x3000
	s_addc_u32 s19, s19, 0
	s_add_u32 s62, s62, 0x4000
	s_addc_u32 s63, s63, 0
	s_add_u32 s2, s2, 0x2000
	s_addc_u32 s3, s3, 0
	global_load_ushort v16, v2, s[18:19]
	global_load_ushort v17, v2, s[18:19] offset:1024
	global_load_ushort v18, v2, s[18:19] offset:2048
	global_load_ushort v19, v2, s[62:63]
	global_load_ushort v20, v2, s[62:63] offset:1024
	global_load_ushort v21, v2, s[2:3]
	s_add_u32 s18, s18, 0x3000
	s_addc_u32 s19, s19, 0
	s_add_u32 s62, s62, 0x4000
	s_addc_u32 s63, s63, 0
	s_add_u32 s2, s2, 0x2000
	s_addc_u32 s3, s3, 0
	global_load_ushort v22, v2, s[18:19]
	global_load_ushort v23, v2, s[18:19] offset:1024
	global_load_ushort v24, v2, s[18:19] offset:2048
	global_load_ushort v25, v2, s[62:63]
	global_load_ushort v26, v2, s[62:63] offset:1024
	global_load_ushort v27, v2, s[2:3]
	s_add_u32 s18, s18, 0x3000
	s_addc_u32 s19, s19, 0
	s_add_u32 s62, s62, 0x4000
	s_addc_u32 s63, s63, 0
	s_add_u32 s2, s2, 0x2000
	s_addc_u32 s3, s3, 0
	global_load_ushort v28, v2, s[18:19]
	global_load_ushort v29, v2, s[18:19] offset:1024
	global_load_ushort v30, v2, s[18:19] offset:2048
	global_load_ushort v31, v2, s[62:63]
	global_load_ushort v32, v2, s[62:63] offset:1024
	global_load_ushort v33, v2, s[2:3]
	s_add_u32 s18, s18, 0x3000
	s_addc_u32 s19, s19, 0
	s_add_u32 s62, s62, 0x4000
	s_addc_u32 s63, s63, 0
	s_add_u32 s2, s2, 0x2000
	s_addc_u32 s3, s3, 0
	global_load_ushort v34, v2, s[18:19]
	global_load_ushort v35, v2, s[18:19] offset:1024
	global_load_ushort v36, v2, s[18:19] offset:2048
	global_load_ushort v37, v2, s[62:63]
	global_load_ushort v38, v2, s[62:63] offset:1024
	global_load_ushort v39, v2, s[2:3]
	s_add_u32 s18, s18, 0x3000
	s_addc_u32 s19, s19, 0
	s_add_u32 s62, s62, 0x4000
	s_addc_u32 s63, s63, 0
	s_add_u32 s2, s2, 0x2000
	s_addc_u32 s3, s3, 0
	global_load_ushort v40, v2, s[18:19]
	global_load_ushort v41, v2, s[18:19] offset:1024
	global_load_ushort v42, v2, s[18:19] offset:2048
	global_load_ushort v43, v2, s[62:63]
	global_load_ushort v44, v2, s[62:63] offset:1024
	global_load_ushort v45, v2, s[2:3]
	s_add_u32 s18, s18, 0x3000
	s_addc_u32 s19, s19, 0
	s_add_u32 s62, s62, 0x4000
	s_addc_u32 s63, s63, 0
	s_add_u32 s2, s2, 0x2000
	s_addc_u32 s3, s3, 0
	global_load_ushort v46, v2, s[18:19]
	global_load_ushort v47, v2, s[18:19] offset:1024
	global_load_ushort v48, v2, s[18:19] offset:2048
	global_load_ushort v49, v2, s[62:63]
	global_load_ushort v50, v2, s[62:63] offset:1024
	global_load_ushort v51, v2, s[2:3]
	s_add_u32 s18, s18, 0x3000
	s_addc_u32 s19, s19, 0
	s_add_u32 s62, s62, 0x4000
	s_addc_u32 s63, s63, 0
	s_add_u32 s2, s2, 0x2000
	s_addc_u32 s3, s3, 0
	global_load_ushort v52, v2, s[18:19]
	global_load_ushort v53, v2, s[18:19] offset:1024
	global_load_ushort v59, v2, s[18:19] offset:2048
	global_load_ushort v60, v2, s[62:63]
	global_load_ushort v61, v2, s[62:63] offset:1024
	global_load_ushort v62, v2, s[2:3]
